# c9 + P3/P4 order swapped for workgroups with bid&8 (GEMM-first) so memory-bound h1 overlaps the small GEMMs
# baseline (speedup 1.0000x reference)
; #define PHASE(k, ...) if (IN(k)) { { __VA_ARGS__ } if (DUPON(k)) { __VA_ARGS__ } SEAM(k); }
; __device__ __forceinline__ void h1_phase(const bf16_t* hq, const bf16_t* hf, const bf16_t* hi, bf16_t* qe_out, bf16_t* intra_out, const float* lb, bf16_t* Ub, float* G, LAS unsigned char* lds, int bid, int Gn) {
;     ...
;     if (bid < 2048) H1_LOAD(bid);
;     for (int u = bid; u < 2048; u += Gn) {
;     const int b = u >> 8, h = (u >> 6) & 3, c = u & 63, t0 = b * SEQ + c * 64, cb = h * 128;
; __global__ void __launch_bounds__(NTHR) mk_fwd(Args a) {
;     ...
;     PHASE(3,
;                  h1_phase(WSB(SL(6)), WSB(SL(7)), WSB(SL(8)), WSB(SL(6)), WSB(SL(7)), (const float*)(ws + WS_LB), WSB(SL(14)), (float*)(ws + WS_G), lds, bid, G);
;                  if (DUPON(21)) h1_phase(WSB(SL(6)), WSB(SL(7)), WSB(SL(8)), (bf16_t*)a.out, (bf16_t*)a.out + SLAB_EL, (const float*)(ws + WS_LB), (bf16_t*)a.out + 2 * SLAB_EL, (float*)(ws + 40 * MiB), lds, bid, G); )
.LBB0_324:
	s_mov_b32 s100, 0
	s_cmp_lt_i32 s84, 4
	s_cselect_b64 s[4:5], -1, 0
	s_cmp_gt_i32 s85, 3
	s_cselect_b64 s[6:7], -1, 0
	s_and_b64 s[4:5], s[4:5], s[6:7]
	s_andn2_b64 vcc, exec, s[4:5]
	s_cbranch_vccnz .LBB0_492
	s_cmpk_lg_i32 s86, 0x100
	s_cbranch_scc1 .Lp34_p3body
	s_cmp_gt_i32 s85, 4
	s_cbranch_scc0 .Lp34_p3body
	s_and_b32 s101, s2, 8
	s_cbranch_scc0 .Lp34_p3body
	s_mov_b32 s100, 1
	s_branch .LBB0_492
.Lp34_p3body:
	s_waitcnt lgkmcnt(0)
	s_add_u32 s36, s30, 0xc000000
	s_addc_u32 s37, s31, 0
	s_add_u32 s38, s30, 0xe000000
	s_addc_u32 s39, s31, 0
	s_add_u32 s42, s30, 0x10000000
	s_addc_u32 s43, s31, 0
	s_cmpk_lt_i32 s2, 0x800
	v_readfirstlane_b32 s3, v254
	s_cselect_b64 s[4:5], -1, 0
	s_cmpk_gt_i32 s2, 0x7ff
	v_lshrrev_b32_e32 v33, 4, v254
	s_cbranch_scc1 .LBB0_327
	s_lshl_b32 s6, s2, 4
	s_lshl_b32 s7, s2, 6
	s_and_b32 s6, s6, 0xfffff000
	s_and_b32 s7, s7, 0xfc0
	s_or_b32 s6, s6, s7
	s_lshl_b32 s7, s2, 1
	v_lshlrev_b32_e32 v0, 3, v254
	s_and_b32 s7, s7, 0x180
	v_and_b32_e32 v0, 0x78, v0
	v_or_b32_e32 v2, s7, v0
	v_or_b32_e32 v0, s6, v33
	v_ashrrev_i32_e32 v1, 31, v0
	v_lshlrev_b64 v[8:9], 10, v[0:1]
	v_lshlrev_b32_e32 v14, 1, v2
	v_or_b32_e32 v8, v8, v14
	v_lshl_add_u64 v[10:11], s[36:37], 0, v[8:9]
	v_lshl_add_u64 v[12:13], s[38:39], 0, v[8:9]
	v_lshl_add_u64 v[16:17], s[42:43], 0, v[8:9]
	v_add_u32_e32 v8, 0x200, v254
	v_lshrrev_b32_e32 v8, 4, v8
	v_add_u32_e32 v8, s6, v8
	v_ashrrev_i32_e32 v9, 31, v8
	v_lshlrev_b64 v[18:19], 10, v[8:9]
	v_or_b32_e32 v18, v18, v14
	v_lshl_add_u64 v[20:21], s[36:37], 0, v[18:19]
	v_lshl_add_u64 v[24:25], s[38:39], 0, v[18:19]
	global_load_dwordx4 v[0:3], v[10:11], off nt
	global_load_dwordx4 v[4:7], v[12:13], off nt
	s_nop 0
	global_load_dwordx4 v[8:11], v[16:17], off nt
	global_load_dwordx4 v[12:15], v[20:21], off nt
	v_lshl_add_u64 v[26:27], s[42:43], 0, v[18:19]
	global_load_dwordx4 v[16:19], v[24:25], off nt
	global_load_dwordx4 v[20:23], v[26:27], off nt

; __device__ __forceinline__ void xcd_barrier(const XcdBarrier& b) {
;     asm volatile("s_waitcnt vmcnt(0)" ::: "memory");
;     __syncthreads();
;     if (threadIdx.x == 0) {
;         unsigned* bar = b.bar;
;         __builtin_amdgcn_s_waitcnt(0);
;         unsigned nloc = b.st[0], nx = b.st[1];
;         if (nloc == 0u) { xcd_barrier_complete(bar, b.x, nloc, nx); b.st[0] = nloc; b.st[1] = nx; }
.LBB0_438:
	s_cmp_eq_u32 s100, 2
	s_cbranch_scc1 .LBB0_555
	s_cmpk_eq_i32 s86, 0x100
	s_cbranch_scc1 .LBB0_492
	s_cmp_lt_i32 s85, 5
	s_cbranch_scc1 .LBB0_492
	s_waitcnt vmcnt(0)
	s_waitcnt vmcnt(0)
	s_barrier
	s_mov_b64 s[4:5], exec
	v_readlane_b32 s6, v255, 1
	v_readlane_b32 s7, v255, 2
	s_and_b64 s[6:7], s[4:5], s[6:7]
	s_mov_b64 exec, s[6:7]
	s_cbranch_execz .LBB0_491
	s_add_i32 s3, 0, 0x23fc0
	v_mov_b32_e32 v0, s3
	s_waitcnt vmcnt(0) expcnt(0) lgkmcnt(0)
	ds_read_b32 v2, v0
	s_add_i32 s3, 0, 0x23fc4
	v_mov_b32_e32 v0, s3
	ds_read_b32 v0, v0
	s_waitcnt lgkmcnt(1)
	v_cmp_ne_u32_e32 vcc, 0, v2
	s_cbranch_vccnz .LBB0_455
	s_add_u32 s6, s30, 0x80200
	s_addc_u32 s7, s31, 0
	s_add_u32 s8, s30, 0x80400
	s_addc_u32 s9, s31, 0
	s_add_u32 s10, s30, 0x80500
	s_addc_u32 s11, s31, 0
	s_add_u32 s12, s30, 0x80600
	s_addc_u32 s13, s31, 0
	s_add_u32 s14, s30, 0x80700
	s_addc_u32 s15, s31, 0
	s_add_u32 s16, s30, 0x80800
	s_addc_u32 s17, s31, 0
	s_add_u32 s18, s30, 0x80900
	s_addc_u32 s19, s31, 0
	s_add_u32 s20, s30, 0x80a00
	s_addc_u32 s21, s31, 0
	s_add_u32 s22, s30, 0x80b00
	s_addc_u32 s23, s31, 0
	s_add_u32 s24, s30, 0x80c00
	s_addc_u32 s25, s31, 0
	s_add_u32 s26, s30, 0x80d00
	s_addc_u32 s27, s31, 0
	s_add_u32 s36, s30, 0x80e00
	s_addc_u32 s37, s31, 0
	s_add_u32 s38, s30, 0x80f00
	s_addc_u32 s39, s31, 0
	s_add_u32 s42, s30, 0x81000
	s_load_dword s3, s[0:1], 0x118
	s_addc_u32 s43, s31, 0
	s_add_u32 s48, s30, 0x81100
	s_addc_u32 s49, s31, 0
	s_add_u32 s54, s30, 0x81200
	s_addc_u32 s55, s31, 0
	s_waitcnt lgkmcnt(0)
	s_mul_i32 s3, s87, s3
	s_add_u32 s58, s30, 0x81300
	s_mul_i32 s3, s3, s86
	s_addc_u32 s59, s31, 0
	s_mov_b32 s28, 1
	v_mov_b32_e32 v16, 0
	s_branch .LBB0_443

;     __host__ __device__ void init(int M, int N, int G_, int c_) { base.init(M, N, G_, c_); }
; #define PHASE(k, ...) if (IN(k)) { { __VA_ARGS__ } if (DUPON(k)) { __VA_ARGS__ } SEAM(k); }
; __global__ void __launch_bounds__(NTHR) mk_fwd(Args a) {
;     ...
;     PHASE(3,
;                  h1_phase(WSB(SL(6)), WSB(SL(7)), WSB(SL(8)), WSB(SL(6)), WSB(SL(7)), (const float*)(ws + WS_LB), WSB(SL(14)), (float*)(ws + WS_G), lds, bid, G);
;                  if (DUPON(21)) h1_phase(WSB(SL(6)), WSB(SL(7)), WSB(SL(8)), (bf16_t*)a.out, (bf16_t*)a.out + SLAB_EL, (const float*)(ws + WS_LB), (bf16_t*)a.out + 2 * SLAB_EL, (float*)(ws + 40 * MiB), lds, bid, G); )
;     PHASE(4,  { pg8::Gemm g{WSB(SL(4)), WSB(WS_WUQ), T, 768, 512}; pg8::StaticOrder S; S.init(T, 768, G, bid);
;                  pg8::EpiRowScale E{(bf16_t*)a.out, 768, (const float*)(ws + WS_RSQ), 1.f / 512.f};
;                  pg8::gemm_phase<pg8::EpiRowScale, pg8::StaticOrder, true, true>(lds, g, S, E); }
;                { pg8::Gemm g{WSB(SL(5)), WSB(WS_WUKV), T, 512, 256, 512}; pg8::StaticOrder S; S.init(T, 512, G, bid);
;                  pg8::EpiRowScale E{WSB(SL(2)), 512, (const float*)(ws + WS_RSKV), 1.f / 256.f};
;                  pg8::gemm_phase<pg8::EpiRowScale, pg8::StaticOrder, true, true>(lds, g, S, E); }
;                { pg8::Gemm g{WSB(WS_WUKV + 512 * 1024), WSB(SL(5)), 512, T, 256, 512}; pg8::StaticOrder S; S.init(512, T, G, bid);
;                  pg8::EpiColScale E{WSB(SL(8)), T, (const float*)(ws + WS_RSKV), 1.f / 256.f};
;                  pg8::gemm_phase<pg8::EpiColScale, pg8::StaticOrder, true, true>(lds, g, S, E); } )
.LBB0_555:
	s_cmp_eq_u32 s100, 1
	s_cbranch_scc0 .Lp34_end
	s_mov_b32 s100, 2
	s_branch .Lp34_p3body
